# grid barrier between the forget cumsum (P2a) and P2b removed: group-prefix pass runs at P3 start on the non-scan WGs (release counter, acquire before attention)
# speedup vs baseline: 1.0253x; 1.0253x over previous
; __device__ __forceinline__ unsigned xb_ld(unsigned* p)              { return __hip_atomic_load(p, __ATOMIC_RELAXED, __HIP_MEMORY_SCOPE_AGENT); }
; __device__ __forceinline__ unsigned xb_add(unsigned* p, unsigned v) { return __hip_atomic_fetch_add(p, v, __ATOMIC_RELAXED, __HIP_MEMORY_SCOPE_AGENT); }
; #define XB_SPIN(cond, bar) do { unsigned _sp = 0; while (cond) { __builtin_amdgcn_s_sleep(1); \
;     if ((++_sp & 255u) == 0u) { if (xb_ld(&(bar)[XB_TMO])) break; if (_sp > XB_SPIN_CAP) { atomicAdd(&(bar)[XB_TMO], 1u); break; } } } } while (0)
; __device__ __forceinline__ void xcd_barrier(const XcdBarrier& b, int tid) {
;     asm volatile("s_waitcnt vmcnt(0)" ::: "memory");
;     __syncthreads();
;     if (tid == 0) {
;         unsigned* bar = b.bar;
;         __builtin_amdgcn_s_waitcnt(0);
;         unsigned nloc = b.st[0], nx = b.st[1];
;         if (nloc == 0u) { xcd_barrier_complete(bar, b.x, nloc, nx); b.st[0] = nloc; b.st[1] = nx; }
;         const unsigned old = xb_add(&bar[XB_XSUB(b.x)], 1u);
;         const unsigned gen = old / nloc;
;         if (old + 1u == (gen + 1u) * nloc) {
;             __builtin_amdgcn_fence(__ATOMIC_RELEASE, "agent");
;             asm volatile("s_waitcnt vmcnt(0)" ::: "memory");
;             const unsigned og = xb_add(&bar[XB_TOP], 1u);
;             const unsigned tg = og / nx;
;             if (og + 1u == (tg + 1u) * nx) xb_add(&bar[XB_TOPGEN], 1u);
;             else XB_SPIN(xb_ld(&bar[XB_TOPGEN]) == tg, bar);
;             __builtin_amdgcn_fence(__ATOMIC_ACQUIRE, "agent");
;             xb_add(&bar[XB_XGEN(b.x)], 1u);
;             asm volatile("s_waitcnt vmcnt(0)" ::: "memory");
;         } else {
;             XB_SPIN(xb_ld(&bar[XB_XGEN(b.x)]) == gen, bar);
;             __builtin_amdgcn_fence(__ATOMIC_ACQUIRE, "agent");
;             asm volatile("s_waitcnt vmcnt(0)" ::: "memory");
;         }
;     }
;     __syncthreads();
; }
.LBB0_256:
	v_mbcnt_lo_u32_b32 v0, -1, 0
	v_mbcnt_hi_u32_b32 v0, -1, v0
	v_readlane_b32 s0, v254, 25
	s_waitcnt vmcnt(0)
	s_nop 0
	v_sub_u32_e32 v0, 0, v0
	v_cmp_eq_u32_e32 vcc, s0, v0
	s_barrier
	s_and_saveexec_b64 s[0:1], vcc
	s_branch .LBB0_308
	s_add_i32 s2, 0, 0x25820
	v_mov_b32_e32 v0, s2
	s_waitcnt vmcnt(0) expcnt(0) lgkmcnt(0)
	ds_read_b32 v2, v0
	s_add_i32 s2, 0, 0x25824
	v_mov_b32_e32 v0, s2
	ds_read_b32 v0, v0
	s_waitcnt lgkmcnt(1)
	v_cmp_ne_u32_e32 vcc, 0, v2
	s_cbranch_vccnz .LBB0_272
	v_readlane_b32 s2, v254, 4
	v_readlane_b32 s3, v254, 5
	s_mul_i32 s33, s3, s97
	s_mul_i32 s33, s33, s2
	s_add_u32 s2, s90, 0x4200
	s_addc_u32 s3, s91, 0
	s_add_u32 s12, s90, 0x4400
	s_addc_u32 s13, s91, 0
	s_add_u32 s16, s90, 0x4500
	s_addc_u32 s17, s91, 0
	s_add_u32 s18, s90, 0x4600
	s_addc_u32 s19, s91, 0
	s_add_u32 s20, s90, 0x4700
	s_addc_u32 s21, s91, 0
	s_add_u32 s22, s90, 0x4800
	s_addc_u32 s23, s91, 0
	s_add_u32 s24, s90, 0x4900
	s_addc_u32 s25, s91, 0
	s_add_u32 s26, s90, 0x4a00
	s_addc_u32 s27, s91, 0
	s_add_u32 s34, s90, 0x4b00
	s_addc_u32 s35, s91, 0
	s_add_u32 s40, s90, 0x4c00
	s_addc_u32 s41, s91, 0
	s_add_u32 s44, s90, 0x4d00
	s_addc_u32 s45, s91, 0
	s_add_u32 s52, s90, 0x4e00
	s_addc_u32 s53, s91, 0
	s_add_u32 s54, s90, 0x4f00
	s_addc_u32 s55, s91, 0
	s_add_u32 s56, s90, 0x5000
	s_addc_u32 s57, s91, 0
	s_add_u32 s58, s90, 0x5100
	s_addc_u32 s59, s91, 0
	s_add_u32 s60, s90, 0x5200
	s_addc_u32 s61, s91, 0
	s_add_u32 s62, s90, 0x5300
	s_addc_u32 s63, s91, 0
	s_mov_b32 s74, 1
	v_mov_b32_e32 v16, 0
	s_branch .LBB0_260

; #define LAS __attribute__((address_space(3)))
; __device__ __forceinline__ void p2b_fgroup(Frame& F, const Args& a, int g) {
;     float* F2 = (float*)(a.ws + WS_F2); const float* PS = (const float*)(a.ws + WS_SSQ);
;     LAS float* sc = (LAS float*)F.lds;
;     const int h = F.tid & 15, part = F.tid >> 4; float s = 0.f;
;     for (int gg = part; gg < g; gg += 32) s += PS[gg * 16 + h];
;     sc[part * 16 + h] = s; __syncthreads();
;     if (F.tid < 16) { float o = 0.f; for (int p = 0; p < 32; ++p) o += sc[p * 16 + F.tid]; sc[512 + F.tid] = o; }
;     __syncthreads();
;     const float off = sc[512 + h];
; #pragma unroll
;     for (int k = 0; k < 2; ++k) { const int r = part + 32 * k; F2[(size_t)h * T + g * 64 + r] += off; }
;     __syncthreads();
; }
; __global__ void __launch_bounds__(NTHR, 2) hybrid_fwd(Args args) {
;     ...
;     {   for (int g = blockIdx.x; g < T / 64; g += F.G) p2b_fgroup(F, args, g);
.LBB0_308:
	s_or_b64 exec, exec, s[0:1]
	s_waitcnt lgkmcnt(0)
	s_barrier
	v_mbcnt_lo_u32_b32 v10, -1, 0
	v_mbcnt_hi_u32_b32 v10, -1, v10
	v_readlane_b32 s0, v254, 25
	s_andn2_b64 vcc, exec, s[4:5]
	v_and_b32_e32 v11, 15, v10
	v_add_u32_e32 v2, s0, v10
	v_ashrrev_i32_e32 v64, 4, v2
	s_branch .LBB0_317
.Lfg_setup:
	v_lshlrev_b32_e32 v0, 16, v11
	v_mov_b32_e32 v1, 0
	v_lshl_add_u64 v[0:1], s[90:91], 0, v[0:1]
	v_ashrrev_i32_e32 v65, 31, v64
	s_add_u32 s2, s90, 0x3e00000
	v_lshl_add_u32 v4, v2, 2, 0
	v_lshl_add_u64 v[0:1], v[64:65], 2, v[0:1]
	s_mov_b64 s[0:1], 0x3c00000
	s_addc_u32 s3, s91, 0
	v_cmp_gt_i32_e32 vcc, 16, v2
	v_lshl_add_u32 v5, v11, 2, 0
	v_lshl_add_u64 v[0:1], v[0:1], 0, s[0:1]
	v_bfi_b32 v6, -16, v2, v10
	v_add_u32_e32 v7, 0x400, v4
	s_mov_b32 s16, s100
	s_branch .LBB0_311
.LBB0_310:
	s_or_b64 exec, exec, s[0:1]
	s_lshl_b32 s0, s16, 6
	s_ashr_i32 s1, s0, 31
	v_lshl_add_u64 v[2:3], s[0:1], 2, v[0:1]
	s_waitcnt lgkmcnt(0)
	s_barrier
	global_load_dword v8, v[2:3], off
	global_load_dword v9, v[2:3], off offset:128
	ds_read_b32 v12, v5 offset:2048
	s_add_i32 s16, s16, s101
	s_cmpk_gt_i32 s16, 0xff
	s_waitcnt vmcnt(1) lgkmcnt(0)
	v_add_f32_e32 v8, v12, v8
	s_waitcnt vmcnt(0)
	v_add_f32_e32 v9, v12, v9
	global_store_dword v[2:3], v8, off
	global_store_dword v[2:3], v9, off offset:128
	s_barrier
	s_cbranch_scc1 .LBB0_317

; __device__ __forceinline__ float bflo(unsigned u) { return __uint_as_float(u << 16); }
; __device__ __forceinline__ float bfhi(unsigned u) { return __uint_as_float(u & 0xffff0000u); }
; __device__ __forceinline__ void p2_qknorm_row(const Args& a, int row, int lane) {
;     bf16* zb = (bf16*)(a.ws + WS_ZB) + (size_t)row * 5120;
; #pragma unroll
;     for (int part = 0; part < 2; ++part) {
;         v4u* p = (v4u*)(zb + part * 1024 + lane * 16); const v4u u0 = p[0], u1 = p[1];
;         float x[16];
; #pragma unroll
;         for (int e = 0; e < 4; ++e) { x[2 * e] = bflo(u0[e]); x[2 * e + 1] = bfhi(u0[e]); x[8 + 2 * e] = bflo(u1[e]); x[8 + 2 * e + 1] = bfhi(u1[e]); }
;         float ss = 0.f;
; #pragma unroll
;         for (int e = 0; e < 16; ++e) ss += x[e] * x[e];
;         ss = quad_sum(ss);
;         const float rstd = (1.f / sqrtf(ss * (1.f / 64.f) + RMS_EPS)) * (part == 0 ? attn_body::C2 : 1.f);
;         const f32x4* g4 = (const f32x4*)(a.in[part == 0 ? 19 : 20] + (lane & 3) * 16);
; __global__ void __launch_bounds__(NTHR, 2) hybrid_fwd(Args args) {
;     ...
;         for (int m = F.gw; m < M; m += F.NGW) p2_qknorm_row(args, m, F.lane);
.LBB0_317:
	s_cmp_eq_u32 s98, 5
	s_cbranch_scc1 .Lfg_late_done
	v_cndmask_b32_e64 v0, 0, 1, s[10:11]
	v_cmp_ne_u32_e64 s[0:1], 1, v0
	s_andn2_b64 vcc, exec, s[10:11]
	v_lshlrev_b32_e32 v0, 4, v10
	v_writelane_b32 v254, s0, 39
	s_nop 1
	v_writelane_b32 v254, s1, 40
	s_nop 0
	v_readlane_b32 s10, v254, 26
	v_readlane_b32 s11, v254, 27
	s_cbranch_vccnz .LBB0_320
	s_mul_i32 s0, s64, 0x2800
	s_mul_hi_i32 s1, s64, 0x2800
	s_add_u32 s0, s90, s0
	v_ashrrev_i32_e32 v1, 31, v0
	v_lshlrev_b32_e32 v2, 6, v10
	v_readlane_b32 s16, v254, 6
	s_addc_u32 s1, s91, s1
	v_and_b32_e32 v4, 0xc0, v2
	v_mov_b32_e32 v5, 0
	v_readlane_b32 s22, v254, 12
	v_readlane_b32 s23, v254, 13
	v_readlane_b32 s24, v254, 14
	v_readlane_b32 s25, v254, 15
	v_lshl_add_u64 v[6:7], v[0:1], 1, s[0:1]
	s_mov_b64 s[0:1], 0xf000000
	v_lshl_add_u64 v[2:3], s[22:23], 0, v[4:5]
	v_lshl_add_u64 v[4:5], s[24:25], 0, v[4:5]
	v_lshl_add_u64 v[6:7], v[6:7], 0, s[0:1]
	s_mul_hi_i32 s1, s10, 0x2800
	s_mul_i32 s0, s10, 0x2800
	v_mov_b32_e32 v1, 0x358637bd
	s_mov_b32 s2, 0xf800000
	v_mov_b32_e32 v12, 0x260
	s_mov_b32 s3, s64
	v_readlane_b32 s17, v254, 7
	v_readlane_b32 s18, v254, 8
	v_readlane_b32 s19, v254, 9
	v_readlane_b32 s20, v254, 10
	v_readlane_b32 s21, v254, 11
	v_readlane_b32 s26, v254, 16
	v_readlane_b32 s27, v254, 17
	v_readlane_b32 s28, v254, 18
	v_readlane_b32 s29, v254, 19
	v_readlane_b32 s30, v254, 20
	v_readlane_b32 s31, v254, 21

; __global__ void __launch_bounds__(NTHR, 2) hybrid_fwd(Args args) {
;     ...
;     {   for (int g = blockIdx.x; g < T / 64; g += F.G) p2b_fgroup(F, args, g);
;     ...
;     {   if ((int)blockIdx.x < NRWB) p3_rwkv_state(F, args);
.Lrw_late_entry:
	s_mov_b32 s98, 5
	s_sub_i32 s100, s94, 64
	s_sub_i32 s101, s97, 64
	v_mbcnt_lo_u32_b32 v10, -1, 0
	v_mbcnt_hi_u32_b32 v10, -1, v10
	v_readlane_b32 s0, v254, 25
	v_and_b32_e32 v11, 15, v10
	s_nop 1
	v_add_u32_e32 v2, s0, v10
	v_ashrrev_i32_e32 v64, 4, v2
	s_branch .Lfg_setup
